# phase D: next unit's K-tile 1 issued in the K-loop tail ahead of the epilogue, counted first wait vmcnt(16), store-draining vmcnt(0) before the loop removed
# baseline (speedup 1.0000x reference)
; DI Params relaunder(const Params& p0) { Params p = p0; size_t z = 0; asm volatile("" : "+s"(z)); p.ws = p0.ws + z; return p; }
; DI void phaseD(const Params& p0, const Slot sl, int layer, unsigned char* lds) {
;   const Params p = relaunder(p0);
;   bf16_t* gl = (bf16_t*)lds;
;   int mt, nt;
;   for (int it = 0; tile_order(sl, it, 4, mt, nt); ++it) {
; #pragma unroll 1
;     for (int which = 0; which < 2; ++which) {
;       const bf16_t* Wg = (which ? p.wupb_t() : p.wupa_t()) + ((long)nt * 256) * 512;
;       const bf16_t* Yg = (which ? p.nz() : p.sbz()) + (long)mt * 256 * 512;
;       const bf16_t* Gg = which ? p.gb() : p.ga();
;       int mt2 = mt, nt2 = nt; bool more = true;
;       if (which) more = tile_order(sl, it + 1, 4, mt2, nt2);
;       const bf16_t* Wn = more ? (which ? p.wupa_t() : p.wupb_t()) + ((long)nt2 * 256) * 512 : Wg;
;       const bf16_t* Yn = more ? (which ? p.sbz() : p.nz()) + (long)mt2 * 256 * 512 : Yg;
;       f32x4 acc[8][4]; zero_acc(acc);
;       gemm_core(Wg, 512, Yg, 512, 512, gl, acc, 64, it > 0 || which, Wn, Yn);
.LBB0_829:
	s_or_b64 exec, exec, s[0:1]
	v_readlane_b32 s4, v254, 62
	v_readlane_b32 s5, v254, 63
	s_mov_b64 s[0:1], 0
	s_andn2_b64 vcc, exec, s[4:5]
	v_cndmask_b32_e64 v0, 0, 1, s[4:5]
	v_cmp_ne_u32_e64 s[44:45], 1, v0
	s_waitcnt lgkmcnt(0)
	s_barrier
	s_mov_b32 s52, 0
	s_cbranch_vccnz .LBB0_905
	s_add_u32 s4, s92, s0
	s_addc_u32 s5, s93, s1
	s_add_u32 s10, s4, 0x8170000
	s_addc_u32 s11, s5, 0
	s_mov_b32 s18, 0
	s_mov_b64 s[12:13], 0
	v_mov_b32_e32 v164, v212
	s_branch .LBB0_832

;     ...
;   const int ra = (wa * 8) * 2 * 1024 + (qi * 4 + quad) * 16, rb = (wb * 4) * 2 * 1024 + (qi * 4 + quad) * 16;
;   unsigned char* buf0 = lds; unsigned char* buf1 = lds + STAGE_B;
;   const int KT = K >> 6;
;   if (!pre) {
;     g_dma(base, off, 0, buf0, w);
;     asm volatile("s_waitcnt vmcnt(0)" ::: "memory");
;     __syncthreads();
;   }
;   for (int kt = 0; kt < KT; kt += 2) {
;     g_dma(base, off, (kt + 1) * kstep, buf1, w);
;     g_compute(buf0, ra, rb, acc);
; DI void zero_acc(f32x4 (&acc)[8][4]) {
; #pragma unroll
;   for (int i = 0; i < 8; ++i)
; #pragma unroll
;     for (int j = 0; j < 4; ++j) acc[i][j] = (f32x4){0.f, 0.f, 0.f, 0.f};
; }
.LBB0_838:
	s_or_b64 vcc, s[16:17], s[46:47]
	s_xor_b64 s[0:1], vcc, -1
	s_xor_b64 s[14:15], s[16:17], -1
	s_or_b64 s[0:1], s[16:17], s[0:1]
	s_and_b64 s[40:41], s[16:17], exec
	v_cndmask_b32_e32 v12, v165, v130, vcc
	s_cselect_b32 s36, 0xfd0000, s33
	s_add_u32 s40, s4, s36
	v_ashrrev_i32_e32 v13, 31, v12
	s_addc_u32 s41, s5, 0
	v_lshlrev_b64 v[12:13], 18, v[12:13]
	v_lshl_add_u64 v[12:13], s[40:41], 0, v[12:13]
	s_and_b64 s[40:41], s[16:17], exec
	s_mov_b32 s24, 0xc170000
	v_cndmask_b32_e32 v10, v166, v132, vcc
	s_cselect_b32 s36, 0x13570000, s24
	s_add_u32 s40, s4, s36
	v_ashrrev_i32_e32 v11, 31, v10
	v_cndmask_b32_e64 v0, v4, v12, s[0:1]
	v_cndmask_b32_e64 v9, v5, v13, s[0:1]
	s_addc_u32 s41, s5, 0
	v_lshlrev_b64 v[4:5], 18, v[10:11]
	v_lshl_add_u64 v[4:5], s[40:41], 0, v[4:5]
	v_cndmask_b32_e64 v2, v2, v4, s[0:1]
	v_cndmask_b32_e64 v3, v3, v5, s[0:1]
	v_and_b32_e32 v4, 48, v8
	v_cndmask_b32_e64 v146, v0, v2, s[8:9]
	s_lshl_b32 s0, s38, 6
	v_lshlrev_b32_e32 v0, 6, v8
	s_movk_i32 s1, 0x3c0
	s_and_b32 s0, s0, 0xffffc000
	v_and_or_b32 v0, v0, s1, v4
	v_or_b32_e32 v172, s0, v0
	s_add_i32 s0, s29, 0x6020
	v_lshl_or_b32 v173, s30, 13, v0
	v_add_u32_e32 v0, s0, v7
	v_add_lshl_u32 v0, v0, v6, 1
	s_add_i32 s0, s29, 0x6000
	v_lshl_add_u64 v[148:149], v[0:1], 0, s[6:7]
	v_add_u32_e32 v0, s0, v7
	v_add_lshl_u32 v0, v0, v6, 1
	s_add_i32 s0, s29, 0x4020
	v_lshl_add_u64 v[150:151], v[0:1], 0, s[6:7]
	v_add_u32_e32 v0, s0, v7
	v_add_lshl_u32 v0, v0, v6, 1
	s_add_i32 s0, s29, 0x4000
	v_lshl_add_u64 v[152:153], v[0:1], 0, s[6:7]
	v_add_u32_e32 v0, s0, v7
	v_add_lshl_u32 v0, v0, v6, 1
	s_add_i32 s0, s29, 0x2020
	v_lshl_add_u64 v[154:155], v[0:1], 0, s[6:7]
	v_add_u32_e32 v0, s0, v7
	v_add_lshl_u32 v0, v0, v6, 1
	s_add_i32 s0, s29, 0x2000
	v_lshl_add_u64 v[156:157], v[0:1], 0, s[6:7]
	v_add_u32_e32 v0, s0, v7
	v_add_lshl_u32 v0, v0, v6, 1
	v_lshl_add_u64 v[158:159], v[0:1], 0, s[6:7]
	v_add3_u32 v0, s29, 32, v7
	v_add_lshl_u32 v0, v0, v6, 1
	v_lshl_add_u64 v[160:161], v[0:1], 0, s[6:7]
	v_add_u32_e32 v0, s29, v7
	v_add_lshl_u32 v0, v0, v6, 1
	v_mov_b32_e32 v2, 0
	s_mov_b32 s28, 0
	v_cndmask_b32_e64 v131, v9, v3, s[8:9]
	v_lshl_add_u64 v[162:163], v[0:1], 0, s[6:7]
	s_movk_i32 s0, 0x80
	v_mov_b32_e32 v3, v2
	v_mov_b32_e32 v4, v2
	v_mov_b32_e32 v5, v2
	v_mov_b32_e32 v34, v2
	v_mov_b32_e32 v35, v2
	v_mov_b32_e32 v36, v2
	v_mov_b32_e32 v37, v2
	v_mov_b32_e32 v62, v2
	v_mov_b32_e32 v63, v2
	v_mov_b32_e32 v64, v2
	v_mov_b32_e32 v65, v2
	v_mov_b32_e32 v98, v2
	v_mov_b32_e32 v99, v2
	v_mov_b32_e32 v100, v2
	v_mov_b32_e32 v101, v2
	v_mov_b32_e32 v6, v2
	v_mov_b32_e32 v7, v2
	v_mov_b32_e32 v8, v2
	v_mov_b32_e32 v9, v2
	v_mov_b32_e32 v38, v2
	v_mov_b32_e32 v39, v2
	v_mov_b32_e32 v40, v2
	v_mov_b32_e32 v41, v2
	v_mov_b32_e32 v70, v2
	v_mov_b32_e32 v71, v2
	v_mov_b32_e32 v72, v2
	v_mov_b32_e32 v73, v2
	v_mov_b32_e32 v102, v2
	v_mov_b32_e32 v103, v2
	v_mov_b32_e32 v104, v2
	v_mov_b32_e32 v105, v2
	v_mov_b32_e32 v10, v2
	v_mov_b32_e32 v11, v2
	v_mov_b32_e32 v12, v2
	v_mov_b32_e32 v13, v2
	v_mov_b32_e32 v42, v2
	v_mov_b32_e32 v43, v2
	v_mov_b32_e32 v44, v2
	v_mov_b32_e32 v45, v2
	v_mov_b32_e32 v74, v2
	v_mov_b32_e32 v75, v2
	v_mov_b32_e32 v76, v2
	v_mov_b32_e32 v77, v2
	v_mov_b32_e32 v106, v2
	v_mov_b32_e32 v107, v2
	v_mov_b32_e32 v108, v2
	v_mov_b32_e32 v109, v2
	v_mov_b32_e32 v14, v2
	v_mov_b32_e32 v15, v2
	v_mov_b32_e32 v16, v2
	v_mov_b32_e32 v17, v2
	v_mov_b32_e32 v46, v2
	v_mov_b32_e32 v47, v2
	v_mov_b32_e32 v48, v2
	v_mov_b32_e32 v49, v2
	v_mov_b32_e32 v78, v2
	v_mov_b32_e32 v79, v2
	v_mov_b32_e32 v80, v2
	v_mov_b32_e32 v81, v2
	v_mov_b32_e32 v110, v2
	v_mov_b32_e32 v111, v2
	v_mov_b32_e32 v112, v2
	v_mov_b32_e32 v113, v2
	v_mov_b32_e32 v18, v2
	v_mov_b32_e32 v19, v2
	v_mov_b32_e32 v20, v2
	v_mov_b32_e32 v21, v2
	v_mov_b32_e32 v50, v2
	v_mov_b32_e32 v51, v2
	v_mov_b32_e32 v52, v2
	v_mov_b32_e32 v53, v2
	v_mov_b32_e32 v82, v2
	v_mov_b32_e32 v83, v2
	v_mov_b32_e32 v84, v2
	v_mov_b32_e32 v85, v2
	v_mov_b32_e32 v114, v2
	v_mov_b32_e32 v115, v2
	v_mov_b32_e32 v116, v2
	v_mov_b32_e32 v117, v2
	v_mov_b32_e32 v22, v2
	v_mov_b32_e32 v23, v2
	v_mov_b32_e32 v24, v2
	v_mov_b32_e32 v25, v2
	v_mov_b32_e32 v54, v2
	v_mov_b32_e32 v55, v2
	v_mov_b32_e32 v56, v2
	v_mov_b32_e32 v57, v2
	v_mov_b32_e32 v86, v2
	v_mov_b32_e32 v87, v2
	v_mov_b32_e32 v88, v2
	v_mov_b32_e32 v89, v2
	v_mov_b32_e32 v118, v2
	v_mov_b32_e32 v119, v2
	v_mov_b32_e32 v120, v2
	v_mov_b32_e32 v121, v2
	v_mov_b32_e32 v26, v2
	v_mov_b32_e32 v27, v2
	v_mov_b32_e32 v28, v2
	v_mov_b32_e32 v29, v2
	v_mov_b32_e32 v58, v2
	v_mov_b32_e32 v59, v2
	v_mov_b32_e32 v60, v2
	v_mov_b32_e32 v61, v2
	v_mov_b32_e32 v90, v2
	v_mov_b32_e32 v91, v2
	v_mov_b32_e32 v92, v2
	v_mov_b32_e32 v93, v2
	v_mov_b32_e32 v122, v2
	v_mov_b32_e32 v123, v2
	v_mov_b32_e32 v124, v2
	v_mov_b32_e32 v125, v2
	v_mov_b32_e32 v30, v2
	v_mov_b32_e32 v31, v2
	v_mov_b32_e32 v32, v2
	v_mov_b32_e32 v33, v2
	v_mov_b32_e32 v66, v2
	v_mov_b32_e32 v67, v2
	v_mov_b32_e32 v68, v2
	v_mov_b32_e32 v69, v2
	v_mov_b32_e32 v94, v2
	v_mov_b32_e32 v95, v2
	v_mov_b32_e32 v96, v2
	v_mov_b32_e32 v97, v2
	v_mov_b32_e32 v126, v2
	v_mov_b32_e32 v127, v2
	v_mov_b32_e32 v128, v2
	v_mov_b32_e32 v129, v2
	v_lshlrev_b32_e32 v152, 1, v133
	v_add_u32_e32 v160, 32, v172
	v_add_u32_e32 v161, 0x10020, v172
	v_add_u32_e32 v162, 0x8020, v173
	v_add_u32_e32 v163, 0x18020, v173
	v_readfirstlane_b32 s38, v142
	v_readfirstlane_b32 s39, v143
	v_readfirstlane_b32 s40, v146
	v_readfirstlane_b32 s41, v131
	v_add_u32_e32 v153, 0x40, v152
	v_add_u32_e32 v154, 0x4000, v152
	v_add_u32_e32 v155, 0x4040, v152
	v_add_u32_e32 v156, 0x8000, v152
	v_add_u32_e32 v157, 0x8040, v152
	v_add_u32_e32 v158, 0xc000, v152
	v_add_u32_e32 v159, 0xc040, v152
	s_add_i32 s42, s27, 32
	s_add_i32 s43, s27, s35
	s_add_u32 s38, s38, 0x80
	s_addc_u32 s39, s39, 0
	s_mov_b32 s53, 0
	s_cmp_eq_u32 s52, 0
	s_cbranch_scc1 .LgD_k1issue
	s_mov_b32 s53, 1
	s_branch .LgD_k1done
; #define G_LDA(dst, ih, ks) _Pragma("unroll") for (int i = 0; i < 4; ++i) dst[i] = mk8(*(const u32x4*)(stage + ra + (((ih) * 4 + i) * 2 + (ks)) * 1024))
; #define G_LDB(dst, ks) _Pragma("unroll") for (int j = 0; j < 4; ++j) dst[j] = mk8(*(const u32x4*)(stage + TILE_B + rb + (j * 2 + (ks)) * 1024))
; #define G_MMA(ih, A, B) do { _Pragma("unroll") for (int i = 0; i < 4; ++i) _Pragma("unroll") for (int j = 0; j < 4; ++j) acc[(ih) * 4 + i][j] = MFMA16(A[i], B[j], acc[(ih) * 4 + i][j]); } while (0)
; DI void g_compute(const unsigned char* stage, int ra, int rb, f32x4 (&acc)[8][4]) {
;   bf16x8 b0[4], b1[4], a0[4], a1[4];
;   G_LDB(b0, 0); G_LDA(a0, 0, 0);
;   __builtin_amdgcn_sched_barrier(0);
;   G_LDA(a1, 1, 0);
;   G_MMA(0, a0, b0);
;   __builtin_amdgcn_sched_barrier(0);
;   G_LDB(b1, 1); G_LDA(a0, 0, 1);
;   G_MMA(1, a1, b0);
;   __builtin_amdgcn_sched_barrier(0);
;   G_LDA(a1, 1, 1);
;   G_MMA(0, a0, b1);
;     ...
;   if (!pre) {
;     g_dma(base, off, 0, buf0, w);
;     asm volatile("s_waitcnt vmcnt(0)" ::: "memory");
;     __syncthreads();
;   }
;   for (int kt = 0; kt < KT; kt += 2) {
;     g_dma(base, off, (kt + 1) * kstep, buf1, w);
;     g_compute(buf0, ra, rb, acc);
.LgD_k1issue:
	s_add_i32 m0, s43, 0x0
	s_nop 0
	global_load_lds_dwordx4 v152, s[38:39]
	s_add_i32 m0, s43, 0x400
	s_nop 0
	global_load_lds_dwordx4 v153, s[38:39]
	s_add_i32 m0, s43, 0x800
	s_nop 0
	global_load_lds_dwordx4 v154, s[38:39]
	s_add_i32 m0, s43, 0xc00
	s_nop 0
	global_load_lds_dwordx4 v155, s[38:39]
	s_add_i32 m0, s43, 0x1000
	s_nop 0
	global_load_lds_dwordx4 v156, s[38:39]
	s_add_i32 m0, s43, 0x1400
	s_nop 0
	global_load_lds_dwordx4 v157, s[38:39]
	s_add_i32 m0, s43, 0x1800
	s_nop 0
	global_load_lds_dwordx4 v158, s[38:39]
	s_add_i32 m0, s43, 0x1c00
	s_nop 0
	global_load_lds_dwordx4 v159, s[38:39]
.LgD_k1done:
	s_add_u32 s38, s38, 0x80
	s_addc_u32 s39, s39, 0
	ds_read_b128 v[174:177], v162
	ds_read_b128 v[178:181], v162 offset:2048
	ds_read_b128 v[182:185], v162 offset:4096
	ds_read_b128 v[186:189], v162 offset:6144
	ds_read_b128 v[190:193], v160
	ds_read_b128 v[194:197], v160 offset:2048
	ds_read_b128 v[198:201], v160 offset:4096
	ds_read_b128 v[202:205], v160 offset:6144
	s_mov_b32 s48, 0
.LgD_loop:
	s_waitcnt lgkmcnt(0)
	v_mfma_f32_16x16x32_bf16 v[126:129], v[190:193], v[174:177], v[126:129]
	v_mfma_f32_16x16x32_bf16 v[94:97], v[190:193], v[178:181], v[94:97]
	ds_read_b128 v[206:209], v160 offset:8192
	v_mfma_f32_16x16x32_bf16 v[66:69], v[190:193], v[182:185], v[66:69]
	v_mfma_f32_16x16x32_bf16 v[30:33], v[190:193], v[186:189], v[30:33]
	v_mfma_f32_16x16x32_bf16 v[122:125], v[194:197], v[174:177], v[122:125]
	ds_read_b128 v[216:219], v160 offset:10240
	v_mfma_f32_16x16x32_bf16 v[90:93], v[194:197], v[178:181], v[90:93]
	v_mfma_f32_16x16x32_bf16 v[58:61], v[194:197], v[182:185], v[58:61]
	v_mfma_f32_16x16x32_bf16 v[26:29], v[194:197], v[186:189], v[26:29]
	ds_read_b128 v[220:223], v160 offset:12288
	v_mfma_f32_16x16x32_bf16 v[118:121], v[198:201], v[174:177], v[118:121]
	v_mfma_f32_16x16x32_bf16 v[86:89], v[198:201], v[178:181], v[86:89]
	v_mfma_f32_16x16x32_bf16 v[54:57], v[198:201], v[182:185], v[54:57]
	ds_read_b128 v[224:227], v160 offset:14336
	v_mfma_f32_16x16x32_bf16 v[22:25], v[198:201], v[186:189], v[22:25]
	v_mfma_f32_16x16x32_bf16 v[114:117], v[202:205], v[174:177], v[114:117]
	v_mfma_f32_16x16x32_bf16 v[82:85], v[202:205], v[178:181], v[82:85]
	v_mfma_f32_16x16x32_bf16 v[50:53], v[202:205], v[182:185], v[50:53]
	v_mfma_f32_16x16x32_bf16 v[18:21], v[202:205], v[186:189], v[18:21]
	s_waitcnt lgkmcnt(0)
	v_mfma_f32_16x16x32_bf16 v[110:113], v[206:209], v[174:177], v[110:113]
	ds_read_b128 v[240:243], v162 offset:1024
	v_mfma_f32_16x16x32_bf16 v[78:81], v[206:209], v[178:181], v[78:81]
	v_mfma_f32_16x16x32_bf16 v[46:49], v[206:209], v[182:185], v[46:49]
	ds_read_b128 v[244:247], v162 offset:3072
	v_mfma_f32_16x16x32_bf16 v[14:17], v[206:209], v[186:189], v[14:17]
	v_mfma_f32_16x16x32_bf16 v[106:109], v[216:219], v[174:177], v[106:109]
	ds_read_b128 v[248:251], v162 offset:5120
	v_mfma_f32_16x16x32_bf16 v[74:77], v[216:219], v[178:181], v[74:77]
	v_mfma_f32_16x16x32_bf16 v[42:45], v[216:219], v[182:185], v[42:45]
	ds_read_b128 v[148:151], v162 offset:7168
	v_mfma_f32_16x16x32_bf16 v[10:13], v[216:219], v[186:189], v[10:13]
	v_mfma_f32_16x16x32_bf16 v[102:105], v[220:223], v[174:177], v[102:105]
	ds_read_b128 v[190:193], v160 offset:1024
	v_mfma_f32_16x16x32_bf16 v[70:73], v[220:223], v[178:181], v[70:73]
	ds_read_b128 v[194:197], v160 offset:3072
	v_mfma_f32_16x16x32_bf16 v[38:41], v[220:223], v[182:185], v[38:41]
	ds_read_b128 v[198:201], v160 offset:5120
	v_mfma_f32_16x16x32_bf16 v[6:9], v[220:223], v[186:189], v[6:9]
	ds_read_b128 v[202:205], v160 offset:7168
	v_mfma_f32_16x16x32_bf16 v[98:101], v[224:227], v[174:177], v[98:101]
	v_mfma_f32_16x16x32_bf16 v[62:65], v[224:227], v[178:181], v[62:65]
	v_mfma_f32_16x16x32_bf16 v[34:37], v[224:227], v[182:185], v[34:37]
	v_mfma_f32_16x16x32_bf16 v[2:5], v[224:227], v[186:189], v[2:5]
	s_waitcnt lgkmcnt(0)
	v_mfma_f32_16x16x32_bf16 v[126:129], v[190:193], v[240:243], v[126:129]
	v_mfma_f32_16x16x32_bf16 v[94:97], v[190:193], v[244:247], v[94:97]
	ds_read_b128 v[206:209], v160 offset:9216
	v_mfma_f32_16x16x32_bf16 v[66:69], v[190:193], v[248:251], v[66:69]
	v_mfma_f32_16x16x32_bf16 v[30:33], v[190:193], v[148:151], v[30:33]
	v_mfma_f32_16x16x32_bf16 v[122:125], v[194:197], v[240:243], v[122:125]
	ds_read_b128 v[216:219], v160 offset:11264
	v_mfma_f32_16x16x32_bf16 v[90:93], v[194:197], v[244:247], v[90:93]
	v_mfma_f32_16x16x32_bf16 v[58:61], v[194:197], v[248:251], v[58:61]
	v_mfma_f32_16x16x32_bf16 v[26:29], v[194:197], v[148:151], v[26:29]
	ds_read_b128 v[220:223], v160 offset:13312
	v_mfma_f32_16x16x32_bf16 v[118:121], v[198:201], v[240:243], v[118:121]
	v_mfma_f32_16x16x32_bf16 v[86:89], v[198:201], v[244:247], v[86:89]
	v_mfma_f32_16x16x32_bf16 v[54:57], v[198:201], v[248:251], v[54:57]
	ds_read_b128 v[224:227], v160 offset:15360
	v_mfma_f32_16x16x32_bf16 v[22:25], v[198:201], v[148:151], v[22:25]
	v_mfma_f32_16x16x32_bf16 v[114:117], v[202:205], v[240:243], v[114:117]
	v_mfma_f32_16x16x32_bf16 v[82:85], v[202:205], v[244:247], v[82:85]
	v_mfma_f32_16x16x32_bf16 v[50:53], v[202:205], v[248:251], v[50:53]
	v_mfma_f32_16x16x32_bf16 v[18:21], v[202:205], v[148:151], v[18:21]
	s_waitcnt lgkmcnt(0)
	s_cmp_eq_u32 s53, 0
	s_cbranch_scc1 .LgD_w0
	s_mov_b32 s53, 0
	s_waitcnt vmcnt(16)
	s_branch .LgD_w1

; #define G_LDA(dst, ih, ks) _Pragma("unroll") for (int i = 0; i < 4; ++i) dst[i] = mk8(*(const u32x4*)(stage + ra + (((ih) * 4 + i) * 2 + (ks)) * 1024))
; #define G_LDB(dst, ks) _Pragma("unroll") for (int j = 0; j < 4; ++j) dst[j] = mk8(*(const u32x4*)(stage + TILE_B + rb + (j * 2 + (ks)) * 1024))
; #define G_MMA(ih, A, B) do { _Pragma("unroll") for (int i = 0; i < 4; ++i) _Pragma("unroll") for (int j = 0; j < 4; ++j) acc[(ih) * 4 + i][j] = MFMA16(A[i], B[j], acc[(ih) * 4 + i][j]); } while (0)
; DI void g_compute(const unsigned char* stage, int ra, int rb, f32x4 (&acc)[8][4]) {
;   bf16x8 b0[4], b1[4], a0[4], a1[4];
;   G_LDB(b0, 0); G_LDA(a0, 0, 0);
;   __builtin_amdgcn_sched_barrier(0);
;   G_LDA(a1, 1, 0);
;   G_MMA(0, a0, b0);
;   __builtin_amdgcn_sched_barrier(0);
;   G_LDB(b1, 1); G_LDA(a0, 0, 1);
;   G_MMA(1, a1, b0);
;   __builtin_amdgcn_sched_barrier(0);
;   G_LDA(a1, 1, 1);
;   G_MMA(0, a0, b1);
;   __builtin_amdgcn_sched_barrier(0);
;   G_MMA(1, a1, b1);
;   __builtin_amdgcn_sched_barrier(0);
; }
;     ...
;     asm volatile("s_waitcnt vmcnt(0)" ::: "memory");
;     __syncthreads();
;     const bool last = kt + 2 >= KT;
;     g_dma(last ? nbase : base, off, last ? 0 : (kt + 2) * kstep, buf0, w);
;     g_compute(buf1, ra, rb, acc);
;     asm volatile("s_waitcnt vmcnt(0)" ::: "memory");
;     __syncthreads();
.LgD_w1:
	s_barrier
	s_add_i32 m0, s42, 0x0
	v_mfma_f32_16x16x32_bf16 v[110:113], v[206:209], v[240:243], v[110:113]
	global_load_lds_dwordx4 v152, s[38:39]
	ds_read_b128 v[174:177], v163
	v_mfma_f32_16x16x32_bf16 v[78:81], v[206:209], v[244:247], v[78:81]
	ds_read_b128 v[178:181], v163 offset:2048
	s_add_i32 m0, s42, 0x400
	v_mfma_f32_16x16x32_bf16 v[46:49], v[206:209], v[248:251], v[46:49]
	global_load_lds_dwordx4 v153, s[38:39]
	ds_read_b128 v[182:185], v163 offset:4096
	v_mfma_f32_16x16x32_bf16 v[14:17], v[206:209], v[148:151], v[14:17]
	ds_read_b128 v[186:189], v163 offset:6144
	s_add_i32 m0, s42, 0x800
	v_mfma_f32_16x16x32_bf16 v[106:109], v[216:219], v[240:243], v[106:109]
	global_load_lds_dwordx4 v154, s[38:39]
	ds_read_b128 v[190:193], v161
	v_mfma_f32_16x16x32_bf16 v[74:77], v[216:219], v[244:247], v[74:77]
	ds_read_b128 v[194:197], v161 offset:2048
	s_add_i32 m0, s42, 0xc00
	v_mfma_f32_16x16x32_bf16 v[42:45], v[216:219], v[248:251], v[42:45]
	global_load_lds_dwordx4 v155, s[38:39]
	ds_read_b128 v[198:201], v161 offset:4096
	v_mfma_f32_16x16x32_bf16 v[10:13], v[216:219], v[148:151], v[10:13]
	ds_read_b128 v[202:205], v161 offset:6144
	s_add_i32 m0, s42, 0x1000
	v_mfma_f32_16x16x32_bf16 v[102:105], v[220:223], v[240:243], v[102:105]
	global_load_lds_dwordx4 v156, s[38:39]
	v_mfma_f32_16x16x32_bf16 v[70:73], v[220:223], v[244:247], v[70:73]
	s_add_i32 m0, s42, 0x1400
	v_mfma_f32_16x16x32_bf16 v[38:41], v[220:223], v[248:251], v[38:41]
	global_load_lds_dwordx4 v157, s[38:39]
	v_mfma_f32_16x16x32_bf16 v[6:9], v[220:223], v[148:151], v[6:9]
	s_add_i32 m0, s42, 0x1800
	v_mfma_f32_16x16x32_bf16 v[98:101], v[224:227], v[240:243], v[98:101]
	global_load_lds_dwordx4 v158, s[38:39]
	v_mfma_f32_16x16x32_bf16 v[62:65], v[224:227], v[244:247], v[62:65]
	s_add_i32 m0, s42, 0x1c00
	v_mfma_f32_16x16x32_bf16 v[34:37], v[224:227], v[248:251], v[34:37]
	global_load_lds_dwordx4 v159, s[38:39]
	v_mfma_f32_16x16x32_bf16 v[2:5], v[224:227], v[148:151], v[2:5]
	s_add_u32 s38, s38, 0x80
	s_addc_u32 s39, s39, 0
	s_waitcnt lgkmcnt(0)
	v_mfma_f32_16x16x32_bf16 v[126:129], v[190:193], v[174:177], v[126:129]
	v_mfma_f32_16x16x32_bf16 v[94:97], v[190:193], v[178:181], v[94:97]
	ds_read_b128 v[206:209], v161 offset:8192
	v_mfma_f32_16x16x32_bf16 v[66:69], v[190:193], v[182:185], v[66:69]
	v_mfma_f32_16x16x32_bf16 v[30:33], v[190:193], v[186:189], v[30:33]
	v_mfma_f32_16x16x32_bf16 v[122:125], v[194:197], v[174:177], v[122:125]
	ds_read_b128 v[216:219], v161 offset:10240
	v_mfma_f32_16x16x32_bf16 v[90:93], v[194:197], v[178:181], v[90:93]
	v_mfma_f32_16x16x32_bf16 v[58:61], v[194:197], v[182:185], v[58:61]
	v_mfma_f32_16x16x32_bf16 v[26:29], v[194:197], v[186:189], v[26:29]
	ds_read_b128 v[220:223], v161 offset:12288
	v_mfma_f32_16x16x32_bf16 v[118:121], v[198:201], v[174:177], v[118:121]
	v_mfma_f32_16x16x32_bf16 v[86:89], v[198:201], v[178:181], v[86:89]
	v_mfma_f32_16x16x32_bf16 v[54:57], v[198:201], v[182:185], v[54:57]
	ds_read_b128 v[224:227], v161 offset:14336
	v_mfma_f32_16x16x32_bf16 v[22:25], v[198:201], v[186:189], v[22:25]
	v_mfma_f32_16x16x32_bf16 v[114:117], v[202:205], v[174:177], v[114:117]
	v_mfma_f32_16x16x32_bf16 v[82:85], v[202:205], v[178:181], v[82:85]
	v_mfma_f32_16x16x32_bf16 v[50:53], v[202:205], v[182:185], v[50:53]
	v_mfma_f32_16x16x32_bf16 v[18:21], v[202:205], v[186:189], v[18:21]
	s_waitcnt lgkmcnt(0)
	v_mfma_f32_16x16x32_bf16 v[110:113], v[206:209], v[174:177], v[110:113]
	ds_read_b128 v[240:243], v163 offset:1024
	v_mfma_f32_16x16x32_bf16 v[78:81], v[206:209], v[178:181], v[78:81]
	v_mfma_f32_16x16x32_bf16 v[46:49], v[206:209], v[182:185], v[46:49]
	ds_read_b128 v[244:247], v163 offset:3072
	v_mfma_f32_16x16x32_bf16 v[14:17], v[206:209], v[186:189], v[14:17]
	v_mfma_f32_16x16x32_bf16 v[106:109], v[216:219], v[174:177], v[106:109]
	ds_read_b128 v[248:251], v163 offset:5120
	v_mfma_f32_16x16x32_bf16 v[74:77], v[216:219], v[178:181], v[74:77]
	v_mfma_f32_16x16x32_bf16 v[42:45], v[216:219], v[182:185], v[42:45]
	ds_read_b128 v[148:151], v163 offset:7168
	v_mfma_f32_16x16x32_bf16 v[10:13], v[216:219], v[186:189], v[10:13]
	v_mfma_f32_16x16x32_bf16 v[102:105], v[220:223], v[174:177], v[102:105]
	ds_read_b128 v[190:193], v161 offset:1024
	v_mfma_f32_16x16x32_bf16 v[70:73], v[220:223], v[178:181], v[70:73]
	ds_read_b128 v[194:197], v161 offset:3072
	v_mfma_f32_16x16x32_bf16 v[38:41], v[220:223], v[182:185], v[38:41]
	ds_read_b128 v[198:201], v161 offset:5120
	v_mfma_f32_16x16x32_bf16 v[6:9], v[220:223], v[186:189], v[6:9]
	ds_read_b128 v[202:205], v161 offset:7168
	v_mfma_f32_16x16x32_bf16 v[98:101], v[224:227], v[174:177], v[98:101]
	v_mfma_f32_16x16x32_bf16 v[62:65], v[224:227], v[178:181], v[62:65]
	v_mfma_f32_16x16x32_bf16 v[34:37], v[224:227], v[182:185], v[34:37]
	v_mfma_f32_16x16x32_bf16 v[2:5], v[224:227], v[186:189], v[2:5]
	s_waitcnt lgkmcnt(0)
	v_mfma_f32_16x16x32_bf16 v[126:129], v[190:193], v[240:243], v[126:129]
	v_mfma_f32_16x16x32_bf16 v[94:97], v[190:193], v[244:247], v[94:97]
	ds_read_b128 v[206:209], v161 offset:9216
	v_mfma_f32_16x16x32_bf16 v[66:69], v[190:193], v[248:251], v[66:69]
	v_mfma_f32_16x16x32_bf16 v[30:33], v[190:193], v[148:151], v[30:33]
	v_mfma_f32_16x16x32_bf16 v[122:125], v[194:197], v[240:243], v[122:125]
	ds_read_b128 v[216:219], v161 offset:11264
	v_mfma_f32_16x16x32_bf16 v[90:93], v[194:197], v[244:247], v[90:93]
	v_mfma_f32_16x16x32_bf16 v[58:61], v[194:197], v[248:251], v[58:61]
	v_mfma_f32_16x16x32_bf16 v[26:29], v[194:197], v[148:151], v[26:29]
	ds_read_b128 v[220:223], v161 offset:13312
	v_mfma_f32_16x16x32_bf16 v[118:121], v[198:201], v[240:243], v[118:121]
	v_mfma_f32_16x16x32_bf16 v[86:89], v[198:201], v[244:247], v[86:89]
	v_mfma_f32_16x16x32_bf16 v[54:57], v[198:201], v[248:251], v[54:57]
	ds_read_b128 v[224:227], v161 offset:15360
	v_mfma_f32_16x16x32_bf16 v[22:25], v[198:201], v[148:151], v[22:25]
	v_mfma_f32_16x16x32_bf16 v[114:117], v[202:205], v[240:243], v[114:117]
	v_mfma_f32_16x16x32_bf16 v[82:85], v[202:205], v[244:247], v[82:85]
	v_mfma_f32_16x16x32_bf16 v[50:53], v[202:205], v[248:251], v[50:53]
	v_mfma_f32_16x16x32_bf16 v[18:21], v[202:205], v[148:151], v[18:21]
	s_waitcnt lgkmcnt(0)
	s_waitcnt vmcnt(0)
	s_barrier
; #define G_LDA(dst, ih, ks) _Pragma("unroll") for (int i = 0; i < 4; ++i) dst[i] = mk8(*(const u32x4*)(stage + ra + (((ih) * 4 + i) * 2 + (ks)) * 1024))
; #define G_LDB(dst, ks) _Pragma("unroll") for (int j = 0; j < 4; ++j) dst[j] = mk8(*(const u32x4*)(stage + TILE_B + rb + (j * 2 + (ks)) * 1024))
; #define G_MMA(ih, A, B) do { _Pragma("unroll") for (int i = 0; i < 4; ++i) _Pragma("unroll") for (int j = 0; j < 4; ++j) acc[(ih) * 4 + i][j] = MFMA16(A[i], B[j], acc[(ih) * 4 + i][j]); } while (0)
; DI void g_compute(const unsigned char* stage, int ra, int rb, f32x4 (&acc)[8][4]) {
;   bf16x8 b0[4], b1[4], a0[4], a1[4];
;   G_LDB(b0, 0); G_LDA(a0, 0, 0);
;   __builtin_amdgcn_sched_barrier(0);
;   G_LDA(a1, 1, 0);
;   G_MMA(0, a0, b0);
;   __builtin_amdgcn_sched_barrier(0);
;   G_LDB(b1, 1); G_LDA(a0, 0, 1);
;   G_MMA(1, a1, b0);
;   __builtin_amdgcn_sched_barrier(0);
;   G_LDA(a1, 1, 1);
;   G_MMA(0, a0, b1);
;   __builtin_amdgcn_sched_barrier(0);
;   G_MMA(1, a1, b1);
;   __builtin_amdgcn_sched_barrier(0);
; }
;     ...
;   for (int kt = 0; kt < KT; kt += 2) {
;     g_dma(base, off, (kt + 1) * kstep, buf1, w);
;     g_compute(buf0, ra, rb, acc);
;     asm volatile("s_waitcnt vmcnt(0)" ::: "memory");
;     __syncthreads();
;     const bool last = kt + 2 >= KT;
;     g_dma(last ? nbase : base, off, last ? 0 : (kt + 2) * kstep, buf0, w);
;     g_compute(buf1, ra, rb, acc);
;     asm volatile("s_waitcnt vmcnt(0)" ::: "memory");
;     __syncthreads();
	s_add_i32 m0, s43, 0x0
	v_mfma_f32_16x16x32_bf16 v[110:113], v[206:209], v[240:243], v[110:113]
	global_load_lds_dwordx4 v152, s[38:39]
	ds_read_b128 v[174:177], v162
	v_mfma_f32_16x16x32_bf16 v[78:81], v[206:209], v[244:247], v[78:81]
	ds_read_b128 v[178:181], v162 offset:2048
	s_add_i32 m0, s43, 0x400
	v_mfma_f32_16x16x32_bf16 v[46:49], v[206:209], v[248:251], v[46:49]
	global_load_lds_dwordx4 v153, s[38:39]
	ds_read_b128 v[182:185], v162 offset:4096
	v_mfma_f32_16x16x32_bf16 v[14:17], v[206:209], v[148:151], v[14:17]
	ds_read_b128 v[186:189], v162 offset:6144
	s_add_i32 m0, s43, 0x800
	v_mfma_f32_16x16x32_bf16 v[106:109], v[216:219], v[240:243], v[106:109]
	global_load_lds_dwordx4 v154, s[38:39]
	ds_read_b128 v[190:193], v160
	v_mfma_f32_16x16x32_bf16 v[74:77], v[216:219], v[244:247], v[74:77]
	ds_read_b128 v[194:197], v160 offset:2048
	s_add_i32 m0, s43, 0xc00
	v_mfma_f32_16x16x32_bf16 v[42:45], v[216:219], v[248:251], v[42:45]
	global_load_lds_dwordx4 v155, s[38:39]
	ds_read_b128 v[198:201], v160 offset:4096
	v_mfma_f32_16x16x32_bf16 v[10:13], v[216:219], v[148:151], v[10:13]
	ds_read_b128 v[202:205], v160 offset:6144
	s_add_i32 m0, s43, 0x1000
	v_mfma_f32_16x16x32_bf16 v[102:105], v[220:223], v[240:243], v[102:105]
	global_load_lds_dwordx4 v156, s[38:39]
	v_mfma_f32_16x16x32_bf16 v[70:73], v[220:223], v[244:247], v[70:73]
	s_add_i32 m0, s43, 0x1400
	v_mfma_f32_16x16x32_bf16 v[38:41], v[220:223], v[248:251], v[38:41]
	global_load_lds_dwordx4 v157, s[38:39]
	v_mfma_f32_16x16x32_bf16 v[6:9], v[220:223], v[148:151], v[6:9]
	s_add_i32 m0, s43, 0x1800
	v_mfma_f32_16x16x32_bf16 v[98:101], v[224:227], v[240:243], v[98:101]
	global_load_lds_dwordx4 v158, s[38:39]
	v_mfma_f32_16x16x32_bf16 v[62:65], v[224:227], v[244:247], v[62:65]
	s_add_i32 m0, s43, 0x1c00
	v_mfma_f32_16x16x32_bf16 v[34:37], v[224:227], v[248:251], v[34:37]
	global_load_lds_dwordx4 v159, s[38:39]
	v_mfma_f32_16x16x32_bf16 v[2:5], v[224:227], v[148:151], v[2:5]
	s_add_u32 s38, s38, 0x80
	s_addc_u32 s39, s39, 0
	s_add_i32 s48, s48, 1
	s_cmp_lt_u32 s48, 3
	s_cbranch_scc1 .LgD_loop
	s_waitcnt lgkmcnt(0)
	v_mfma_f32_16x16x32_bf16 v[126:129], v[190:193], v[174:177], v[126:129]
	v_mfma_f32_16x16x32_bf16 v[94:97], v[190:193], v[178:181], v[94:97]
	ds_read_b128 v[206:209], v160 offset:8192
	v_mfma_f32_16x16x32_bf16 v[66:69], v[190:193], v[182:185], v[66:69]
	v_mfma_f32_16x16x32_bf16 v[30:33], v[190:193], v[186:189], v[30:33]
	v_mfma_f32_16x16x32_bf16 v[122:125], v[194:197], v[174:177], v[122:125]
	ds_read_b128 v[216:219], v160 offset:10240
	v_mfma_f32_16x16x32_bf16 v[90:93], v[194:197], v[178:181], v[90:93]
	v_mfma_f32_16x16x32_bf16 v[58:61], v[194:197], v[182:185], v[58:61]
	v_mfma_f32_16x16x32_bf16 v[26:29], v[194:197], v[186:189], v[26:29]
	ds_read_b128 v[220:223], v160 offset:12288
	v_mfma_f32_16x16x32_bf16 v[118:121], v[198:201], v[174:177], v[118:121]
	v_mfma_f32_16x16x32_bf16 v[86:89], v[198:201], v[178:181], v[86:89]
	v_mfma_f32_16x16x32_bf16 v[54:57], v[198:201], v[182:185], v[54:57]
	ds_read_b128 v[224:227], v160 offset:14336
	v_mfma_f32_16x16x32_bf16 v[22:25], v[198:201], v[186:189], v[22:25]
	v_mfma_f32_16x16x32_bf16 v[114:117], v[202:205], v[174:177], v[114:117]
	v_mfma_f32_16x16x32_bf16 v[82:85], v[202:205], v[178:181], v[82:85]
	v_mfma_f32_16x16x32_bf16 v[50:53], v[202:205], v[182:185], v[50:53]
	v_mfma_f32_16x16x32_bf16 v[18:21], v[202:205], v[186:189], v[18:21]
	s_waitcnt lgkmcnt(0)
	v_mfma_f32_16x16x32_bf16 v[110:113], v[206:209], v[174:177], v[110:113]
	ds_read_b128 v[240:243], v162 offset:1024
	v_mfma_f32_16x16x32_bf16 v[78:81], v[206:209], v[178:181], v[78:81]
	v_mfma_f32_16x16x32_bf16 v[46:49], v[206:209], v[182:185], v[46:49]
	ds_read_b128 v[244:247], v162 offset:3072
	v_mfma_f32_16x16x32_bf16 v[14:17], v[206:209], v[186:189], v[14:17]
	v_mfma_f32_16x16x32_bf16 v[106:109], v[216:219], v[174:177], v[106:109]
	ds_read_b128 v[248:251], v162 offset:5120
	v_mfma_f32_16x16x32_bf16 v[74:77], v[216:219], v[178:181], v[74:77]
	v_mfma_f32_16x16x32_bf16 v[42:45], v[216:219], v[182:185], v[42:45]
	ds_read_b128 v[148:151], v162 offset:7168
	v_mfma_f32_16x16x32_bf16 v[10:13], v[216:219], v[186:189], v[10:13]
	v_mfma_f32_16x16x32_bf16 v[102:105], v[220:223], v[174:177], v[102:105]
	ds_read_b128 v[190:193], v160 offset:1024
	v_mfma_f32_16x16x32_bf16 v[70:73], v[220:223], v[178:181], v[70:73]
	ds_read_b128 v[194:197], v160 offset:3072
	v_mfma_f32_16x16x32_bf16 v[38:41], v[220:223], v[182:185], v[38:41]
	ds_read_b128 v[198:201], v160 offset:5120
	v_mfma_f32_16x16x32_bf16 v[6:9], v[220:223], v[186:189], v[6:9]
	ds_read_b128 v[202:205], v160 offset:7168
	v_mfma_f32_16x16x32_bf16 v[98:101], v[224:227], v[174:177], v[98:101]
	v_mfma_f32_16x16x32_bf16 v[62:65], v[224:227], v[178:181], v[62:65]
	v_mfma_f32_16x16x32_bf16 v[34:37], v[224:227], v[182:185], v[34:37]
	v_mfma_f32_16x16x32_bf16 v[2:5], v[224:227], v[186:189], v[2:5]
	s_waitcnt lgkmcnt(0)
	v_mfma_f32_16x16x32_bf16 v[126:129], v[190:193], v[240:243], v[126:129]
	v_mfma_f32_16x16x32_bf16 v[94:97], v[190:193], v[244:247], v[94:97]
	ds_read_b128 v[206:209], v160 offset:9216
	v_mfma_f32_16x16x32_bf16 v[66:69], v[190:193], v[248:251], v[66:69]
	v_mfma_f32_16x16x32_bf16 v[30:33], v[190:193], v[148:151], v[30:33]
	v_mfma_f32_16x16x32_bf16 v[122:125], v[194:197], v[240:243], v[122:125]
	ds_read_b128 v[216:219], v160 offset:11264
	v_mfma_f32_16x16x32_bf16 v[90:93], v[194:197], v[244:247], v[90:93]
	v_mfma_f32_16x16x32_bf16 v[58:61], v[194:197], v[248:251], v[58:61]
	v_mfma_f32_16x16x32_bf16 v[26:29], v[194:197], v[148:151], v[26:29]
	ds_read_b128 v[220:223], v160 offset:13312
	v_mfma_f32_16x16x32_bf16 v[118:121], v[198:201], v[240:243], v[118:121]
	v_mfma_f32_16x16x32_bf16 v[86:89], v[198:201], v[244:247], v[86:89]
	v_mfma_f32_16x16x32_bf16 v[54:57], v[198:201], v[248:251], v[54:57]
	ds_read_b128 v[224:227], v160 offset:15360
	v_mfma_f32_16x16x32_bf16 v[22:25], v[198:201], v[148:151], v[22:25]
	v_mfma_f32_16x16x32_bf16 v[114:117], v[202:205], v[240:243], v[114:117]
	v_mfma_f32_16x16x32_bf16 v[82:85], v[202:205], v[244:247], v[82:85]
	v_mfma_f32_16x16x32_bf16 v[50:53], v[202:205], v[248:251], v[50:53]
	v_mfma_f32_16x16x32_bf16 v[18:21], v[202:205], v[148:151], v[18:21]
	s_waitcnt lgkmcnt(0)
	s_waitcnt vmcnt(0)
	s_barrier
; #define G_LDA(dst, ih, ks) _Pragma("unroll") for (int i = 0; i < 4; ++i) dst[i] = mk8(*(const u32x4*)(stage + ra + (((ih) * 4 + i) * 2 + (ks)) * 1024))
; #define G_LDB(dst, ks) _Pragma("unroll") for (int j = 0; j < 4; ++j) dst[j] = mk8(*(const u32x4*)(stage + TILE_B + rb + (j * 2 + (ks)) * 1024))
; #define G_MMA(ih, A, B) do { _Pragma("unroll") for (int i = 0; i < 4; ++i) _Pragma("unroll") for (int j = 0; j < 4; ++j) acc[(ih) * 4 + i][j] = MFMA16(A[i], B[j], acc[(ih) * 4 + i][j]); } while (0)
; DI void g_compute(const unsigned char* stage, int ra, int rb, f32x4 (&acc)[8][4]) {
;   bf16x8 b0[4], b1[4], a0[4], a1[4];
;   G_LDB(b0, 0); G_LDA(a0, 0, 0);
;   __builtin_amdgcn_sched_barrier(0);
;   G_LDA(a1, 1, 0);
;   G_MMA(0, a0, b0);
;   __builtin_amdgcn_sched_barrier(0);
;   G_LDB(b1, 1); G_LDA(a0, 0, 1);
;   G_MMA(1, a1, b0);
;   __builtin_amdgcn_sched_barrier(0);
;   G_LDA(a1, 1, 1);
;   G_MMA(0, a0, b1);
;   __builtin_amdgcn_sched_barrier(0);
;   G_MMA(1, a1, b1);
;   __builtin_amdgcn_sched_barrier(0);
; }
;     ...
;     const bool last = kt + 2 >= KT;
;     g_dma(last ? nbase : base, off, last ? 0 : (kt + 2) * kstep, buf0, w);
;     g_compute(buf1, ra, rb, acc);
;     asm volatile("s_waitcnt vmcnt(0)" ::: "memory");
;     __syncthreads();
	s_add_i32 m0, s42, 0x0
	v_mfma_f32_16x16x32_bf16 v[110:113], v[206:209], v[240:243], v[110:113]
	global_load_lds_dwordx4 v152, s[40:41]
	ds_read_b128 v[174:177], v163
	v_mfma_f32_16x16x32_bf16 v[78:81], v[206:209], v[244:247], v[78:81]
	ds_read_b128 v[178:181], v163 offset:2048
	s_add_i32 m0, s42, 0x400
	v_mfma_f32_16x16x32_bf16 v[46:49], v[206:209], v[248:251], v[46:49]
	global_load_lds_dwordx4 v153, s[40:41]
	ds_read_b128 v[182:185], v163 offset:4096
	v_mfma_f32_16x16x32_bf16 v[14:17], v[206:209], v[148:151], v[14:17]
	ds_read_b128 v[186:189], v163 offset:6144
	s_add_i32 m0, s42, 0x800
	v_mfma_f32_16x16x32_bf16 v[106:109], v[216:219], v[240:243], v[106:109]
	global_load_lds_dwordx4 v154, s[40:41]
	ds_read_b128 v[190:193], v161
	v_mfma_f32_16x16x32_bf16 v[74:77], v[216:219], v[244:247], v[74:77]
	ds_read_b128 v[194:197], v161 offset:2048
	s_add_i32 m0, s42, 0xc00
	v_mfma_f32_16x16x32_bf16 v[42:45], v[216:219], v[248:251], v[42:45]
	global_load_lds_dwordx4 v155, s[40:41]
	ds_read_b128 v[198:201], v161 offset:4096
	v_mfma_f32_16x16x32_bf16 v[10:13], v[216:219], v[148:151], v[10:13]
	ds_read_b128 v[202:205], v161 offset:6144
	s_add_i32 m0, s42, 0x1000
	v_mfma_f32_16x16x32_bf16 v[102:105], v[220:223], v[240:243], v[102:105]
	global_load_lds_dwordx4 v156, s[40:41]
	v_mfma_f32_16x16x32_bf16 v[70:73], v[220:223], v[244:247], v[70:73]
	s_add_i32 m0, s42, 0x1400
	v_mfma_f32_16x16x32_bf16 v[38:41], v[220:223], v[248:251], v[38:41]
	global_load_lds_dwordx4 v157, s[40:41]
	v_mfma_f32_16x16x32_bf16 v[6:9], v[220:223], v[148:151], v[6:9]
	s_add_i32 m0, s42, 0x1800
	v_mfma_f32_16x16x32_bf16 v[98:101], v[224:227], v[240:243], v[98:101]
	global_load_lds_dwordx4 v158, s[40:41]
	v_mfma_f32_16x16x32_bf16 v[62:65], v[224:227], v[244:247], v[62:65]
	s_add_i32 m0, s42, 0x1c00
	v_mfma_f32_16x16x32_bf16 v[34:37], v[224:227], v[248:251], v[34:37]
	global_load_lds_dwordx4 v159, s[40:41]
	v_mfma_f32_16x16x32_bf16 v[2:5], v[224:227], v[148:151], v[2:5]
	s_add_u32 s40, s40, 0x80
	s_addc_u32 s41, s41, 0
	s_waitcnt lgkmcnt(0)
	v_mfma_f32_16x16x32_bf16 v[126:129], v[190:193], v[174:177], v[126:129]
	v_mfma_f32_16x16x32_bf16 v[94:97], v[190:193], v[178:181], v[94:97]
	ds_read_b128 v[206:209], v161 offset:8192
	v_mfma_f32_16x16x32_bf16 v[66:69], v[190:193], v[182:185], v[66:69]
	v_mfma_f32_16x16x32_bf16 v[30:33], v[190:193], v[186:189], v[30:33]
	v_mfma_f32_16x16x32_bf16 v[122:125], v[194:197], v[174:177], v[122:125]
	ds_read_b128 v[216:219], v161 offset:10240
	v_mfma_f32_16x16x32_bf16 v[90:93], v[194:197], v[178:181], v[90:93]
	v_mfma_f32_16x16x32_bf16 v[58:61], v[194:197], v[182:185], v[58:61]
	v_mfma_f32_16x16x32_bf16 v[26:29], v[194:197], v[186:189], v[26:29]
	ds_read_b128 v[220:223], v161 offset:12288
	v_mfma_f32_16x16x32_bf16 v[118:121], v[198:201], v[174:177], v[118:121]
	v_mfma_f32_16x16x32_bf16 v[86:89], v[198:201], v[178:181], v[86:89]
	v_mfma_f32_16x16x32_bf16 v[54:57], v[198:201], v[182:185], v[54:57]
	ds_read_b128 v[224:227], v161 offset:14336
	v_mfma_f32_16x16x32_bf16 v[22:25], v[198:201], v[186:189], v[22:25]
	v_mfma_f32_16x16x32_bf16 v[114:117], v[202:205], v[174:177], v[114:117]
	v_mfma_f32_16x16x32_bf16 v[82:85], v[202:205], v[178:181], v[82:85]
	v_mfma_f32_16x16x32_bf16 v[50:53], v[202:205], v[182:185], v[50:53]
	v_mfma_f32_16x16x32_bf16 v[18:21], v[202:205], v[186:189], v[18:21]
	s_waitcnt lgkmcnt(0)
	v_mfma_f32_16x16x32_bf16 v[110:113], v[206:209], v[174:177], v[110:113]
	ds_read_b128 v[240:243], v163 offset:1024
	v_mfma_f32_16x16x32_bf16 v[78:81], v[206:209], v[178:181], v[78:81]
	v_mfma_f32_16x16x32_bf16 v[46:49], v[206:209], v[182:185], v[46:49]
	ds_read_b128 v[244:247], v163 offset:3072
	v_mfma_f32_16x16x32_bf16 v[14:17], v[206:209], v[186:189], v[14:17]
	v_mfma_f32_16x16x32_bf16 v[106:109], v[216:219], v[174:177], v[106:109]
	ds_read_b128 v[248:251], v163 offset:5120
	v_mfma_f32_16x16x32_bf16 v[74:77], v[216:219], v[178:181], v[74:77]
	v_mfma_f32_16x16x32_bf16 v[42:45], v[216:219], v[182:185], v[42:45]
	ds_read_b128 v[148:151], v163 offset:7168
	v_mfma_f32_16x16x32_bf16 v[10:13], v[216:219], v[186:189], v[10:13]
	v_mfma_f32_16x16x32_bf16 v[102:105], v[220:223], v[174:177], v[102:105]
	ds_read_b128 v[190:193], v161 offset:1024
	v_mfma_f32_16x16x32_bf16 v[70:73], v[220:223], v[178:181], v[70:73]
	ds_read_b128 v[194:197], v161 offset:3072
	v_mfma_f32_16x16x32_bf16 v[38:41], v[220:223], v[182:185], v[38:41]
	ds_read_b128 v[198:201], v161 offset:5120
	v_mfma_f32_16x16x32_bf16 v[6:9], v[220:223], v[186:189], v[6:9]
	ds_read_b128 v[202:205], v161 offset:7168
	v_mfma_f32_16x16x32_bf16 v[98:101], v[224:227], v[174:177], v[98:101]
	v_mfma_f32_16x16x32_bf16 v[62:65], v[224:227], v[178:181], v[62:65]
	v_mfma_f32_16x16x32_bf16 v[34:37], v[224:227], v[182:185], v[34:37]
	v_mfma_f32_16x16x32_bf16 v[2:5], v[224:227], v[186:189], v[2:5]
	s_waitcnt lgkmcnt(0)
	v_mfma_f32_16x16x32_bf16 v[126:129], v[190:193], v[240:243], v[126:129]
	v_mfma_f32_16x16x32_bf16 v[94:97], v[190:193], v[244:247], v[94:97]
	ds_read_b128 v[206:209], v161 offset:9216
	v_mfma_f32_16x16x32_bf16 v[66:69], v[190:193], v[248:251], v[66:69]
	v_mfma_f32_16x16x32_bf16 v[30:33], v[190:193], v[148:151], v[30:33]
	v_mfma_f32_16x16x32_bf16 v[122:125], v[194:197], v[240:243], v[122:125]
	ds_read_b128 v[216:219], v161 offset:11264
	v_mfma_f32_16x16x32_bf16 v[90:93], v[194:197], v[244:247], v[90:93]
	v_mfma_f32_16x16x32_bf16 v[58:61], v[194:197], v[248:251], v[58:61]
	v_mfma_f32_16x16x32_bf16 v[26:29], v[194:197], v[148:151], v[26:29]
	ds_read_b128 v[220:223], v161 offset:13312
	v_mfma_f32_16x16x32_bf16 v[118:121], v[198:201], v[240:243], v[118:121]
	v_mfma_f32_16x16x32_bf16 v[86:89], v[198:201], v[244:247], v[86:89]
	v_mfma_f32_16x16x32_bf16 v[54:57], v[198:201], v[248:251], v[54:57]
	ds_read_b128 v[224:227], v161 offset:15360
	v_mfma_f32_16x16x32_bf16 v[22:25], v[198:201], v[148:151], v[22:25]
	v_mfma_f32_16x16x32_bf16 v[114:117], v[202:205], v[240:243], v[114:117]
	v_mfma_f32_16x16x32_bf16 v[82:85], v[202:205], v[244:247], v[82:85]
	v_mfma_f32_16x16x32_bf16 v[50:53], v[202:205], v[248:251], v[50:53]
	v_mfma_f32_16x16x32_bf16 v[18:21], v[202:205], v[148:151], v[18:21]
	s_waitcnt lgkmcnt(0)
	s_waitcnt vmcnt(0)
	s_barrier
; DI unsigned pk2(float lo, float hi) { f32x2 v = {lo, hi}; bf16x2_t b = __builtin_convertvector(v, bf16x2_t); return __builtin_bit_cast(unsigned, b); }
; DI float bflo(unsigned u) { return __uint_as_float(u << 16); }
; DI float bfhi(unsigned u) { return __uint_as_float(u & 0xffff0000u); }
; DI int my_tid() { int t = threadIdx.x; asm volatile("" : "+v"(t)); return t; }
;     ...
;   for (int kt = 0; kt < KT; kt += 2) {
;     g_dma(base, off, (kt + 1) * kstep, buf1, w);
; DI void phaseD(const Params& p0, const Slot sl, int layer, unsigned char* lds) {
;     ...
;       const int tid = my_tid(), lane = tid & 63, w = tid >> 6, wa = w >> 2, wb = w & 3, qi = lane & 15, quad = lane >> 4;
; #pragma unroll
;       for (int j = 0; j < 4; ++j) {
;         const long tok = (long)mt * 256 + wb * 64 + j * 16 + qi;
; #pragma unroll
;         for (int i = 0; i < 8; ++i) {
;           const long off = tok * 1024 + nt * 256 + wa * 128 + i * 16 + quad * 4;
;           const u32x2 xg = *(const u32x2*)(Gg + off);
;           const f32x4 v = acc[i][j];
;           float o0 = bflo(xg[0]) * v[0], o1 = bfhi(xg[0]) * v[1], o2 = bflo(xg[1]) * v[2], o3 = bfhi(xg[1]) * v[3];
;           if (which) { const u32x2 a = *(const u32x2*)(p.merged() + off); o0 += bflo(a[0]); o1 += bfhi(a[0]); o2 += bflo(a[1]); o3 += bfhi(a[1]); }
;           *(u32x2*)(p.merged() + off) = (u32x2){pk2(o0, o1), pk2(o2, o3)};
;           if ((i & 3) == 3) asm volatile("" ::: "memory");
;         }
;       }
	s_add_i32 m0, s43, 0x0
	v_mfma_f32_16x16x32_bf16 v[110:113], v[206:209], v[240:243], v[110:113]
	global_load_lds_dwordx4 v152, s[40:41]
	v_mfma_f32_16x16x32_bf16 v[78:81], v[206:209], v[244:247], v[78:81]
	s_add_i32 m0, s43, 0x400
	v_mfma_f32_16x16x32_bf16 v[46:49], v[206:209], v[248:251], v[46:49]
	global_load_lds_dwordx4 v153, s[40:41]
	v_mfma_f32_16x16x32_bf16 v[14:17], v[206:209], v[148:151], v[14:17]
	s_add_i32 m0, s43, 0x800
	v_mfma_f32_16x16x32_bf16 v[106:109], v[216:219], v[240:243], v[106:109]
	global_load_lds_dwordx4 v154, s[40:41]
	v_mfma_f32_16x16x32_bf16 v[74:77], v[216:219], v[244:247], v[74:77]
	s_add_i32 m0, s43, 0xc00
	v_mfma_f32_16x16x32_bf16 v[42:45], v[216:219], v[248:251], v[42:45]
	global_load_lds_dwordx4 v155, s[40:41]
	v_mfma_f32_16x16x32_bf16 v[10:13], v[216:219], v[148:151], v[10:13]
	s_add_i32 m0, s43, 0x1000
	v_mfma_f32_16x16x32_bf16 v[102:105], v[220:223], v[240:243], v[102:105]
	global_load_lds_dwordx4 v156, s[40:41]
	v_mfma_f32_16x16x32_bf16 v[70:73], v[220:223], v[244:247], v[70:73]
	s_add_i32 m0, s43, 0x1400
	v_mfma_f32_16x16x32_bf16 v[38:41], v[220:223], v[248:251], v[38:41]
	global_load_lds_dwordx4 v157, s[40:41]
	v_mfma_f32_16x16x32_bf16 v[6:9], v[220:223], v[148:151], v[6:9]
	s_add_i32 m0, s43, 0x1800
	v_mfma_f32_16x16x32_bf16 v[98:101], v[224:227], v[240:243], v[98:101]
	global_load_lds_dwordx4 v158, s[40:41]
	v_mfma_f32_16x16x32_bf16 v[62:65], v[224:227], v[244:247], v[62:65]
	s_add_i32 m0, s43, 0x1c00
	v_mfma_f32_16x16x32_bf16 v[34:37], v[224:227], v[248:251], v[34:37]
	global_load_lds_dwordx4 v159, s[40:41]
	v_mfma_f32_16x16x32_bf16 v[2:5], v[224:227], v[148:151], v[2:5]
	s_add_u32 s40, s40, 0x80
	s_addc_u32 s41, s41, 0
	s_mov_b32 s52, 1
	s_nop 7
	s_nop 3
	s_cmp_lg_u64 s[16:17], 0
	s_mov_b32 s50, 0x19570000
	s_cselect_b32 s50, 0x15570000, s50
	s_add_u32 s50, s4, s50
	s_addc_u32 s51, s5, 0
	v_and_b32_e32 v200, 0xc0, v210
	v_and_b32_e32 v201, 15, v210
	v_or3_b32 v200, v138, v200, v201
	v_ashrrev_i32_e32 v201, 1, v210
	v_and_b32_e32 v201, 0xffffff80, v201
	v_add_u32_e32 v201, v201, v140
	v_lshlrev_b32_e32 v160, 11, v200
	v_lshl_add_u32 v160, v201, 1, v160
	v_bfe_u32 v205, v210, 4, 2
	v_and_b32_e32 v200, 1, v205
	v_lshl_add_u32 v160, v200, 5, v160
	v_lshrrev_b32_e32 v200, 1, v205
	v_lshl_add_u32 v160, v200, 4, v160
	v_add_u32_e32 v161, 0x8000, v160
	v_add_u32_e32 v163, 0x10000, v160
	v_add_u32_e32 v167, 0x18000, v160
	s_cmp_lg_u64 s[14:15], 0
	s_cbranch_scc1 .LeD_p1
	global_load_dwordx4 v[168:171], v160, s[50:51]
	global_load_dwordx4 v[172:175], v160, s[50:51] offset:64
	global_load_dwordx4 v[176:179], v160, s[50:51] offset:128
	global_load_dwordx4 v[180:183], v160, s[50:51] offset:192
	global_load_dwordx4 v[184:187], v161, s[50:51]
	global_load_dwordx4 v[188:191], v161, s[50:51] offset:64
	global_load_dwordx4 v[192:195], v161, s[50:51] offset:128
	global_load_dwordx4 v[196:199], v161, s[50:51] offset:192
	global_load_dwordx4 v[216:219], v163, s[50:51]
	global_load_dwordx4 v[220:223], v163, s[50:51] offset:64
	global_load_dwordx4 v[224:227], v163, s[50:51] offset:128
	global_load_dwordx4 v[240:243], v163, s[50:51] offset:192
	global_load_dwordx4 v[244:247], v167, s[50:51]
	global_load_dwordx4 v[248:251], v167, s[50:51] offset:64
	s_waitcnt vmcnt(13)
	v_permlane16_swap_b32_e32 v168, v170
	v_permlane16_swap_b32_e32 v169, v171
	v_lshlrev_b32_e32 v206, 16, v168
	v_and_b32_e32 v207, 0xffff0000, v168
	v_lshlrev_b32_e32 v208, 16, v169
	v_and_b32_e32 v209, 0xffff0000, v169
	v_pk_mul_f32 v[126:127], v[126:127], v[206:207]
	v_pk_mul_f32 v[128:129], v[128:129], v[208:209]
	v_lshlrev_b32_e32 v206, 16, v170
	v_and_b32_e32 v207, 0xffff0000, v170
	v_lshlrev_b32_e32 v208, 16, v171
	v_and_b32_e32 v209, 0xffff0000, v171
	v_pk_mul_f32 v[122:123], v[122:123], v[206:207]
	v_pk_mul_f32 v[124:125], v[124:125], v[208:209]
	global_load_dwordx4 v[168:171], v167, s[50:51] offset:128
	s_waitcnt vmcnt(13)
	v_permlane16_swap_b32_e32 v172, v174
	v_permlane16_swap_b32_e32 v173, v175
	v_lshlrev_b32_e32 v206, 16, v172
	v_and_b32_e32 v207, 0xffff0000, v172
	v_lshlrev_b32_e32 v208, 16, v173
	v_and_b32_e32 v209, 0xffff0000, v173
	v_pk_mul_f32 v[118:119], v[118:119], v[206:207]
	v_pk_mul_f32 v[120:121], v[120:121], v[208:209]
	v_lshlrev_b32_e32 v206, 16, v174
	v_and_b32_e32 v207, 0xffff0000, v174
	v_lshlrev_b32_e32 v208, 16, v175
	v_and_b32_e32 v209, 0xffff0000, v175
	v_pk_mul_f32 v[114:115], v[114:115], v[206:207]
	v_pk_mul_f32 v[116:117], v[116:117], v[208:209]
	global_load_dwordx4 v[172:175], v167, s[50:51] offset:192
	v_cvt_pk_bf16_f32 v152, v118, v119
	v_cvt_pk_bf16_f32 v153, v120, v121
	v_cvt_pk_bf16_f32 v154, v114, v115
	v_cvt_pk_bf16_f32 v155, v116, v117
	s_nop 1
	v_permlane16_swap_b32_e32 v152, v154
	v_permlane16_swap_b32_e32 v153, v155
	global_store_dwordx4 v160, v[152:155], s[10:11] offset:64
	v_cvt_pk_bf16_f32 v156, v126, v127
	v_cvt_pk_bf16_f32 v157, v128, v129
	v_cvt_pk_bf16_f32 v158, v122, v123
	v_cvt_pk_bf16_f32 v159, v124, v125
	s_nop 1
	v_permlane16_swap_b32_e32 v156, v158
	v_permlane16_swap_b32_e32 v157, v159
	global_store_dwordx4 v160, v[156:159], s[10:11]
	s_waitcnt vmcnt(15)
	v_permlane16_swap_b32_e32 v176, v178
	v_permlane16_swap_b32_e32 v177, v179
	v_lshlrev_b32_e32 v206, 16, v176
	v_and_b32_e32 v207, 0xffff0000, v176
	v_lshlrev_b32_e32 v208, 16, v177
	v_and_b32_e32 v209, 0xffff0000, v177
	v_pk_mul_f32 v[110:111], v[110:111], v[206:207]
	v_pk_mul_f32 v[112:113], v[112:113], v[208:209]
	v_lshlrev_b32_e32 v206, 16, v178
	v_and_b32_e32 v207, 0xffff0000, v178
	v_lshlrev_b32_e32 v208, 16, v179
	v_and_b32_e32 v209, 0xffff0000, v179
	v_pk_mul_f32 v[106:107], v[106:107], v[206:207]
	v_pk_mul_f32 v[108:109], v[108:109], v[208:209]
	v_cvt_pk_bf16_f32 v152, v110, v111
	v_cvt_pk_bf16_f32 v153, v112, v113
	v_cvt_pk_bf16_f32 v154, v106, v107
	v_cvt_pk_bf16_f32 v155, v108, v109
	s_nop 1
	v_permlane16_swap_b32_e32 v152, v154
	v_permlane16_swap_b32_e32 v153, v155
	global_store_dwordx4 v160, v[152:155], s[10:11] offset:128
	s_waitcnt vmcnt(15)
; DI unsigned pk2(float lo, float hi) { f32x2 v = {lo, hi}; bf16x2_t b = __builtin_convertvector(v, bf16x2_t); return __builtin_bit_cast(unsigned, b); }
; DI float bflo(unsigned u) { return __uint_as_float(u << 16); }
; DI float bfhi(unsigned u) { return __uint_as_float(u & 0xffff0000u); }
; DI void phaseD(const Params& p0, const Slot sl, int layer, unsigned char* lds) {
;     ...
; #pragma unroll
;       for (int j = 0; j < 4; ++j) {
;         const long tok = (long)mt * 256 + wb * 64 + j * 16 + qi;
; #pragma unroll
;         for (int i = 0; i < 8; ++i) {
;           const long off = tok * 1024 + nt * 256 + wa * 128 + i * 16 + quad * 4;
;           const u32x2 xg = *(const u32x2*)(Gg + off);
;           const f32x4 v = acc[i][j];
;           float o0 = bflo(xg[0]) * v[0], o1 = bfhi(xg[0]) * v[1], o2 = bflo(xg[1]) * v[2], o3 = bfhi(xg[1]) * v[3];
;           if (which) { const u32x2 a = *(const u32x2*)(p.merged() + off); o0 += bflo(a[0]); o1 += bfhi(a[0]); o2 += bflo(a[1]); o3 += bfhi(a[1]); }
;           *(u32x2*)(p.merged() + off) = (u32x2){pk2(o0, o1), pk2(o2, o3)};
;           if ((i & 3) == 3) asm volatile("" ::: "memory");
;         }
;       }
	v_permlane16_swap_b32_e32 v180, v182
	v_permlane16_swap_b32_e32 v181, v183
	v_lshlrev_b32_e32 v206, 16, v180
	v_and_b32_e32 v207, 0xffff0000, v180
	v_lshlrev_b32_e32 v208, 16, v181
	v_and_b32_e32 v209, 0xffff0000, v181
	v_pk_mul_f32 v[102:103], v[102:103], v[206:207]
	v_pk_mul_f32 v[104:105], v[104:105], v[208:209]
	v_lshlrev_b32_e32 v206, 16, v182
	v_and_b32_e32 v207, 0xffff0000, v182
	v_lshlrev_b32_e32 v208, 16, v183
	v_and_b32_e32 v209, 0xffff0000, v183
	v_pk_mul_f32 v[98:99], v[98:99], v[206:207]
	v_pk_mul_f32 v[100:101], v[100:101], v[208:209]
	v_cvt_pk_bf16_f32 v156, v102, v103
	v_cvt_pk_bf16_f32 v157, v104, v105
	v_cvt_pk_bf16_f32 v158, v98, v99
	v_cvt_pk_bf16_f32 v159, v100, v101
	s_nop 1
	v_permlane16_swap_b32_e32 v156, v158
	v_permlane16_swap_b32_e32 v157, v159
	global_store_dwordx4 v160, v[156:159], s[10:11] offset:192
	s_waitcnt vmcnt(15)
	v_permlane16_swap_b32_e32 v184, v186
	v_permlane16_swap_b32_e32 v185, v187
	v_lshlrev_b32_e32 v206, 16, v184
	v_and_b32_e32 v207, 0xffff0000, v184
	v_lshlrev_b32_e32 v208, 16, v185
	v_and_b32_e32 v209, 0xffff0000, v185
	v_pk_mul_f32 v[94:95], v[94:95], v[206:207]
	v_pk_mul_f32 v[96:97], v[96:97], v[208:209]
	v_lshlrev_b32_e32 v206, 16, v186
	v_and_b32_e32 v207, 0xffff0000, v186
	v_lshlrev_b32_e32 v208, 16, v187
	v_and_b32_e32 v209, 0xffff0000, v187
	v_pk_mul_f32 v[90:91], v[90:91], v[206:207]
	v_pk_mul_f32 v[92:93], v[92:93], v[208:209]
	v_cvt_pk_bf16_f32 v152, v94, v95
	v_cvt_pk_bf16_f32 v153, v96, v97
	v_cvt_pk_bf16_f32 v154, v90, v91
	v_cvt_pk_bf16_f32 v155, v92, v93
	s_nop 1
	v_permlane16_swap_b32_e32 v152, v154
	v_permlane16_swap_b32_e32 v153, v155
	global_store_dwordx4 v161, v[152:155], s[10:11]
	s_waitcnt vmcnt(15)
	v_permlane16_swap_b32_e32 v188, v190
	v_permlane16_swap_b32_e32 v189, v191
	v_lshlrev_b32_e32 v206, 16, v188
	v_and_b32_e32 v207, 0xffff0000, v188
	v_lshlrev_b32_e32 v208, 16, v189
	v_and_b32_e32 v209, 0xffff0000, v189
	v_pk_mul_f32 v[86:87], v[86:87], v[206:207]
	v_pk_mul_f32 v[88:89], v[88:89], v[208:209]
	v_lshlrev_b32_e32 v206, 16, v190
	v_and_b32_e32 v207, 0xffff0000, v190
	v_lshlrev_b32_e32 v208, 16, v191
	v_and_b32_e32 v209, 0xffff0000, v191
	v_pk_mul_f32 v[82:83], v[82:83], v[206:207]
	v_pk_mul_f32 v[84:85], v[84:85], v[208:209]
	v_cvt_pk_bf16_f32 v156, v86, v87
	v_cvt_pk_bf16_f32 v157, v88, v89
	v_cvt_pk_bf16_f32 v158, v82, v83
	v_cvt_pk_bf16_f32 v159, v84, v85
	s_nop 1
	v_permlane16_swap_b32_e32 v156, v158
	v_permlane16_swap_b32_e32 v157, v159
	global_store_dwordx4 v161, v[156:159], s[10:11] offset:64
	s_waitcnt vmcnt(15)
	v_permlane16_swap_b32_e32 v192, v194
	v_permlane16_swap_b32_e32 v193, v195
	v_lshlrev_b32_e32 v206, 16, v192
	v_and_b32_e32 v207, 0xffff0000, v192
	v_lshlrev_b32_e32 v208, 16, v193
	v_and_b32_e32 v209, 0xffff0000, v193
	v_pk_mul_f32 v[78:79], v[78:79], v[206:207]
	v_pk_mul_f32 v[80:81], v[80:81], v[208:209]
	v_lshlrev_b32_e32 v206, 16, v194
	v_and_b32_e32 v207, 0xffff0000, v194
	v_lshlrev_b32_e32 v208, 16, v195
	v_and_b32_e32 v209, 0xffff0000, v195
	v_pk_mul_f32 v[74:75], v[74:75], v[206:207]
	v_pk_mul_f32 v[76:77], v[76:77], v[208:209]
	v_cvt_pk_bf16_f32 v152, v78, v79
	v_cvt_pk_bf16_f32 v153, v80, v81
	v_cvt_pk_bf16_f32 v154, v74, v75
	v_cvt_pk_bf16_f32 v155, v76, v77
	s_nop 1
	v_permlane16_swap_b32_e32 v152, v154
	v_permlane16_swap_b32_e32 v153, v155
	global_store_dwordx4 v161, v[152:155], s[10:11] offset:128
	s_waitcnt vmcnt(15)
	v_permlane16_swap_b32_e32 v196, v198
	v_permlane16_swap_b32_e32 v197, v199
	v_lshlrev_b32_e32 v206, 16, v196
	v_and_b32_e32 v207, 0xffff0000, v196
	v_lshlrev_b32_e32 v208, 16, v197
	v_and_b32_e32 v209, 0xffff0000, v197
	v_pk_mul_f32 v[70:71], v[70:71], v[206:207]
	v_pk_mul_f32 v[72:73], v[72:73], v[208:209]
	v_lshlrev_b32_e32 v206, 16, v198
	v_and_b32_e32 v207, 0xffff0000, v198
	v_lshlrev_b32_e32 v208, 16, v199
	v_and_b32_e32 v209, 0xffff0000, v199
	v_pk_mul_f32 v[62:63], v[62:63], v[206:207]
	v_pk_mul_f32 v[64:65], v[64:65], v[208:209]
	v_cvt_pk_bf16_f32 v156, v70, v71
	v_cvt_pk_bf16_f32 v157, v72, v73
	v_cvt_pk_bf16_f32 v158, v62, v63
	v_cvt_pk_bf16_f32 v159, v64, v65
	s_nop 1
	v_permlane16_swap_b32_e32 v156, v158
	v_permlane16_swap_b32_e32 v157, v159
	global_store_dwordx4 v161, v[156:159], s[10:11] offset:192
	s_waitcnt vmcnt(15)
	v_permlane16_swap_b32_e32 v216, v218
	v_permlane16_swap_b32_e32 v217, v219
	v_lshlrev_b32_e32 v206, 16, v216
	v_and_b32_e32 v207, 0xffff0000, v216
	v_lshlrev_b32_e32 v208, 16, v217
	v_and_b32_e32 v209, 0xffff0000, v217
	v_pk_mul_f32 v[66:67], v[66:67], v[206:207]
	v_pk_mul_f32 v[68:69], v[68:69], v[208:209]
	v_lshlrev_b32_e32 v206, 16, v218
	v_and_b32_e32 v207, 0xffff0000, v218
	v_lshlrev_b32_e32 v208, 16, v219
	v_and_b32_e32 v209, 0xffff0000, v219
	v_pk_mul_f32 v[58:59], v[58:59], v[206:207]
	v_pk_mul_f32 v[60:61], v[60:61], v[208:209]
	v_cvt_pk_bf16_f32 v152, v66, v67
	v_cvt_pk_bf16_f32 v153, v68, v69
	v_cvt_pk_bf16_f32 v154, v58, v59
	v_cvt_pk_bf16_f32 v155, v60, v61
	s_nop 1
	v_permlane16_swap_b32_e32 v152, v154
	v_permlane16_swap_b32_e32 v153, v155
	global_store_dwordx4 v163, v[152:155], s[10:11]
	s_waitcnt vmcnt(15)
; DI unsigned pk2(float lo, float hi) { f32x2 v = {lo, hi}; bf16x2_t b = __builtin_convertvector(v, bf16x2_t); return __builtin_bit_cast(unsigned, b); }
; DI float bflo(unsigned u) { return __uint_as_float(u << 16); }
; DI float bfhi(unsigned u) { return __uint_as_float(u & 0xffff0000u); }
; DI void phaseD(const Params& p0, const Slot sl, int layer, unsigned char* lds) {
;     ...
; #pragma unroll
;       for (int j = 0; j < 4; ++j) {
;         const long tok = (long)mt * 256 + wb * 64 + j * 16 + qi;
; #pragma unroll
;         for (int i = 0; i < 8; ++i) {
;           const long off = tok * 1024 + nt * 256 + wa * 128 + i * 16 + quad * 4;
;           const u32x2 xg = *(const u32x2*)(Gg + off);
;           const f32x4 v = acc[i][j];
;           float o0 = bflo(xg[0]) * v[0], o1 = bfhi(xg[0]) * v[1], o2 = bflo(xg[1]) * v[2], o3 = bfhi(xg[1]) * v[3];
;           if (which) { const u32x2 a = *(const u32x2*)(p.merged() + off); o0 += bflo(a[0]); o1 += bfhi(a[0]); o2 += bflo(a[1]); o3 += bfhi(a[1]); }
;           *(u32x2*)(p.merged() + off) = (u32x2){pk2(o0, o1), pk2(o2, o3)};
;           if ((i & 3) == 3) asm volatile("" ::: "memory");
;         }
;       }
	v_permlane16_swap_b32_e32 v220, v222
	v_permlane16_swap_b32_e32 v221, v223
	v_lshlrev_b32_e32 v206, 16, v220
	v_and_b32_e32 v207, 0xffff0000, v220
	v_lshlrev_b32_e32 v208, 16, v221
	v_and_b32_e32 v209, 0xffff0000, v221
	v_pk_mul_f32 v[54:55], v[54:55], v[206:207]
	v_pk_mul_f32 v[56:57], v[56:57], v[208:209]
	v_lshlrev_b32_e32 v206, 16, v222
	v_and_b32_e32 v207, 0xffff0000, v222
	v_lshlrev_b32_e32 v208, 16, v223
	v_and_b32_e32 v209, 0xffff0000, v223
	v_pk_mul_f32 v[50:51], v[50:51], v[206:207]
	v_pk_mul_f32 v[52:53], v[52:53], v[208:209]
	v_cvt_pk_bf16_f32 v156, v54, v55
	v_cvt_pk_bf16_f32 v157, v56, v57
	v_cvt_pk_bf16_f32 v158, v50, v51
	v_cvt_pk_bf16_f32 v159, v52, v53
	s_nop 1
	v_permlane16_swap_b32_e32 v156, v158
	v_permlane16_swap_b32_e32 v157, v159
	global_store_dwordx4 v163, v[156:159], s[10:11] offset:64
	s_waitcnt vmcnt(15)
	v_permlane16_swap_b32_e32 v224, v226
	v_permlane16_swap_b32_e32 v225, v227
	v_lshlrev_b32_e32 v206, 16, v224
	v_and_b32_e32 v207, 0xffff0000, v224
	v_lshlrev_b32_e32 v208, 16, v225
	v_and_b32_e32 v209, 0xffff0000, v225
	v_pk_mul_f32 v[46:47], v[46:47], v[206:207]
	v_pk_mul_f32 v[48:49], v[48:49], v[208:209]
	v_lshlrev_b32_e32 v206, 16, v226
	v_and_b32_e32 v207, 0xffff0000, v226
	v_lshlrev_b32_e32 v208, 16, v227
	v_and_b32_e32 v209, 0xffff0000, v227
	v_pk_mul_f32 v[42:43], v[42:43], v[206:207]
	v_pk_mul_f32 v[44:45], v[44:45], v[208:209]
	v_cvt_pk_bf16_f32 v152, v46, v47
	v_cvt_pk_bf16_f32 v153, v48, v49
	v_cvt_pk_bf16_f32 v154, v42, v43
	v_cvt_pk_bf16_f32 v155, v44, v45
	s_nop 1
	v_permlane16_swap_b32_e32 v152, v154
	v_permlane16_swap_b32_e32 v153, v155
	global_store_dwordx4 v163, v[152:155], s[10:11] offset:128
	s_waitcnt vmcnt(15)
	v_permlane16_swap_b32_e32 v240, v242
	v_permlane16_swap_b32_e32 v241, v243
	v_lshlrev_b32_e32 v206, 16, v240
	v_and_b32_e32 v207, 0xffff0000, v240
	v_lshlrev_b32_e32 v208, 16, v241
	v_and_b32_e32 v209, 0xffff0000, v241
	v_pk_mul_f32 v[38:39], v[38:39], v[206:207]
	v_pk_mul_f32 v[40:41], v[40:41], v[208:209]
	v_lshlrev_b32_e32 v206, 16, v242
	v_and_b32_e32 v207, 0xffff0000, v242
	v_lshlrev_b32_e32 v208, 16, v243
	v_and_b32_e32 v209, 0xffff0000, v243
	v_pk_mul_f32 v[34:35], v[34:35], v[206:207]
	v_pk_mul_f32 v[36:37], v[36:37], v[208:209]
	v_cvt_pk_bf16_f32 v156, v38, v39
	v_cvt_pk_bf16_f32 v157, v40, v41
	v_cvt_pk_bf16_f32 v158, v34, v35
	v_cvt_pk_bf16_f32 v159, v36, v37
	s_nop 1
	v_permlane16_swap_b32_e32 v156, v158
	v_permlane16_swap_b32_e32 v157, v159
	global_store_dwordx4 v163, v[156:159], s[10:11] offset:192
	s_waitcnt vmcnt(15)
	v_permlane16_swap_b32_e32 v244, v246
	v_permlane16_swap_b32_e32 v245, v247
	v_lshlrev_b32_e32 v206, 16, v244
	v_and_b32_e32 v207, 0xffff0000, v244
	v_lshlrev_b32_e32 v208, 16, v245
	v_and_b32_e32 v209, 0xffff0000, v245
	v_pk_mul_f32 v[30:31], v[30:31], v[206:207]
	v_pk_mul_f32 v[32:33], v[32:33], v[208:209]
	v_lshlrev_b32_e32 v206, 16, v246
	v_and_b32_e32 v207, 0xffff0000, v246
	v_lshlrev_b32_e32 v208, 16, v247
	v_and_b32_e32 v209, 0xffff0000, v247
	v_pk_mul_f32 v[26:27], v[26:27], v[206:207]
	v_pk_mul_f32 v[28:29], v[28:29], v[208:209]
	v_cvt_pk_bf16_f32 v152, v30, v31
	v_cvt_pk_bf16_f32 v153, v32, v33
	v_cvt_pk_bf16_f32 v154, v26, v27
	v_cvt_pk_bf16_f32 v155, v28, v29
	s_nop 1
	v_permlane16_swap_b32_e32 v152, v154
	v_permlane16_swap_b32_e32 v153, v155
	global_store_dwordx4 v167, v[152:155], s[10:11]
	s_waitcnt vmcnt(15)
	v_permlane16_swap_b32_e32 v248, v250
	v_permlane16_swap_b32_e32 v249, v251
	v_lshlrev_b32_e32 v206, 16, v248
	v_and_b32_e32 v207, 0xffff0000, v248
	v_lshlrev_b32_e32 v208, 16, v249
	v_and_b32_e32 v209, 0xffff0000, v249
	v_pk_mul_f32 v[22:23], v[22:23], v[206:207]
	v_pk_mul_f32 v[24:25], v[24:25], v[208:209]
	v_lshlrev_b32_e32 v206, 16, v250
	v_and_b32_e32 v207, 0xffff0000, v250
	v_lshlrev_b32_e32 v208, 16, v251
	v_and_b32_e32 v209, 0xffff0000, v251
	v_pk_mul_f32 v[18:19], v[18:19], v[206:207]
	v_pk_mul_f32 v[20:21], v[20:21], v[208:209]
	v_cvt_pk_bf16_f32 v156, v22, v23
	v_cvt_pk_bf16_f32 v157, v24, v25
	v_cvt_pk_bf16_f32 v158, v18, v19
	v_cvt_pk_bf16_f32 v159, v20, v21
	s_nop 1
	v_permlane16_swap_b32_e32 v156, v158
	v_permlane16_swap_b32_e32 v157, v159
	global_store_dwordx4 v167, v[156:159], s[10:11] offset:64
	s_waitcnt vmcnt(15)
	v_permlane16_swap_b32_e32 v168, v170
	v_permlane16_swap_b32_e32 v169, v171
	v_lshlrev_b32_e32 v206, 16, v168
	v_and_b32_e32 v207, 0xffff0000, v168
	v_lshlrev_b32_e32 v208, 16, v169
	v_and_b32_e32 v209, 0xffff0000, v169
	v_pk_mul_f32 v[14:15], v[14:15], v[206:207]
	v_pk_mul_f32 v[16:17], v[16:17], v[208:209]
	v_lshlrev_b32_e32 v206, 16, v170
	v_and_b32_e32 v207, 0xffff0000, v170
	v_lshlrev_b32_e32 v208, 16, v171
	v_and_b32_e32 v209, 0xffff0000, v171
	v_pk_mul_f32 v[10:11], v[10:11], v[206:207]
	v_pk_mul_f32 v[12:13], v[12:13], v[208:209]
	v_cvt_pk_bf16_f32 v152, v14, v15
	v_cvt_pk_bf16_f32 v153, v16, v17
	v_cvt_pk_bf16_f32 v154, v10, v11
	v_cvt_pk_bf16_f32 v155, v12, v13
	s_nop 1
	v_permlane16_swap_b32_e32 v152, v154
	v_permlane16_swap_b32_e32 v153, v155
	global_store_dwordx4 v167, v[152:155], s[10:11] offset:128
	s_waitcnt vmcnt(15)
	v_permlane16_swap_b32_e32 v172, v174
	v_permlane16_swap_b32_e32 v173, v175
	v_lshlrev_b32_e32 v206, 16, v172
	v_and_b32_e32 v207, 0xffff0000, v172
	v_lshlrev_b32_e32 v208, 16, v173
	v_and_b32_e32 v209, 0xffff0000, v173
	v_pk_mul_f32 v[6:7], v[6:7], v[206:207]
	v_pk_mul_f32 v[8:9], v[8:9], v[208:209]
	v_lshlrev_b32_e32 v206, 16, v174
	v_and_b32_e32 v207, 0xffff0000, v174
	v_lshlrev_b32_e32 v208, 16, v175
	v_and_b32_e32 v209, 0xffff0000, v175
	v_pk_mul_f32 v[2:3], v[2:3], v[206:207]
	v_pk_mul_f32 v[4:5], v[4:5], v[208:209]
	v_cvt_pk_bf16_f32 v156, v6, v7
	v_cvt_pk_bf16_f32 v157, v8, v9
	v_cvt_pk_bf16_f32 v158, v2, v3
	v_cvt_pk_bf16_f32 v159, v4, v5
	s_nop 1
	v_permlane16_swap_b32_e32 v156, v158
	v_permlane16_swap_b32_e32 v157, v159
	global_store_dwordx4 v167, v[156:159], s[10:11] offset:192
	s_branch .Lmy_D_cont
